# attention: V prefetch stays in flight across softmax/PV in the fast path (MMAK waits count the 12 younger V loads)
# baseline (speedup 1.0000x reference)
; #define ATT_LOADK(buf, grp) do { _Pragma("unroll") for (int tt = 0; tt < 3; ++tt) { int ki = kbase + 16 * ((grp) * 3 + tt); ki = ki < 0 ? 0 : (ki > a.m - 1 ? a.m - 1 : ki); \
;             const bf16_t* kp = kcol + (size_t)ki * 128; \
;             _Pragma("unroll") for (int ks = 0; ks < 4; ++ks) Kf[buf][tt][ks] = *(const bf16x8*)(kp + 32 * ks); } } while (0)
; #define ATT_MMAK(buf, grp) do { _Pragma("unroll") for (int tt = 0; tt < 3; ++tt) { f32x4 acc_ = (f32x4){0.f, 0.f, 0.f, 0.f}; \
;             _Pragma("unroll") for (int ks = 0; ks < 4; ++ks) acc_ = __builtin_amdgcn_mfma_f32_16x16x32_bf16(Kf[buf][tt][ks], Qf[ks], acc_, 0, 0, 0); sa[(grp) * 3 + tt] = acc_; } } while (0)
; __device__ __forceinline__ void attn_phase(LAS unsigned char* lds, bf16_t* qkv, float* lse, const float* biasT, int G) {
;     ...
;         const size_t tokq = (size_t)(a.pos0 + a.r + ((16 * w4 + li) << a.dsh));
;         const int pbase = a.seq_base + a.r * a.m;
;         bf16_t* qp = qkv + ((size_t)a.head * M_TOK + pbase + a.i0 + 16 * w4 + li) * 128;
;         bf16x8 Qf[4];
; #pragma unroll
;         for (int ks = 0; ks < 4; ++ks) Qf[ks] = *(const bf16x8*)(qp + 32 * ks + 8 * lg);
;         const int kbase = a.i0 - 64 + 16 * w4 + li;
;         const bf16_t* kcol = qkv + ((size_t)(12 + a.head) * M_TOK + pbase) * 128 + 8 * lg;
;         f32x4 sa[10];
;         bf16x8 Kf[2][3][4];
;     ...
;         ATT_LOADK(0, 0); ATT_LOADK(1, 1);
;         __builtin_amdgcn_sched_barrier(0);
;         ATT_MMAK(0, 0);
;         __builtin_amdgcn_sched_barrier(0);
;         ATT_LOADK(0, 2);
;         if (pairn < 4608) { const AttnItem an = attn_item(pairn * 2 + half); attn_load_v(an, qkv, ht, vreg); }
.LBB0_425:
	s_or_b64 exec, exec, s[0:1]
	s_mul_i32 s0, s10, 0xfffffd00
	s_add_i32 s0, s0, s9
	s_lshl_b32 s1, s0, 6
	s_and_b32 s9, s1, 0xffffe000
	s_cmpk_lt_i32 s0, 0x200
	s_cselect_b32 s0, 13, 14
	s_cselect_b32 s9, s9, 0x8000
	s_ashr_i32 s11, s10, 1
	s_and_b32 s12, s11, -2
	s_sub_i32 s11, s0, s12
	s_sub_i32 s30, s1, s9
	s_ashr_i32 s96, s30, s11
	s_lshl_b32 s31, s96, s11
	s_sub_i32 s13, s30, s31
	s_add_i32 s16, s31, s9
	s_mul_hi_i32 s0, s10, 0xc000
	s_ashr_i32 s18, s16, 31
	s_ashr_i32 s1, s13, 31
	s_mul_i32 s17, s10, 0xc000
	v_mov_b32_e32 v3, s0
	s_add_u32 s0, s13, s16
	v_or_b32_e32 v2, s17, v184
	s_addc_u32 s1, s1, s18
	v_lshl_add_u64 v[2:3], s[0:1], 0, v[2:3]
	v_readlane_b32 s0, v250, 21
	s_add_i32 s15, s13, s0
	s_add_i32 s0, s10, 12
	s_add_i32 s17, s17, 0x90000
	v_lshlrev_b64 v[2:3], 8, v[2:3]
	s_mul_hi_i32 s1, s0, 0xc000
	s_add_u32 s0, s17, s16
	v_lshl_add_u64 v[194:195], s[92:93], 0, v[2:3]
	v_mov_b32_e32 v191, v1
	s_addc_u32 s1, s1, s18
	v_lshl_add_u64 v[2:3], v[194:195], 0, v[190:191]
	s_lshl_b64 s[0:1], s[0:1], 8
	global_load_dwordx4 v[96:99], v[2:3], off
	global_load_dwordx4 v[92:95], v[2:3], off offset:64
	global_load_dwordx4 v[88:91], v[2:3], off offset:128
	global_load_dwordx4 v[52:55], v[2:3], off offset:192
	v_add_u32_e32 v0, s15, v216
	v_lshl_add_u64 v[2:3], v[186:187], 0, s[0:1]
	s_bfm_b32 s0, s11, 0
	v_min_i32_e32 v56, s0, v0
	v_ashrrev_i32_e32 v57, 31, v56
	v_lshlrev_b64 v[56:57], 7, v[56:57]
	v_cmp_lt_i32_e32 vcc, -1, v0
	s_movk_i32 s1, 0xffef
	v_add_u32_e32 v58, 48, v0
	v_cndmask_b32_e32 v57, 0, v57, vcc
	v_cndmask_b32_e32 v56, 0, v56, vcc
	v_lshl_add_u64 v[56:57], v[56:57], 1, v[2:3]
	global_load_dwordx4 v[68:71], v[56:57], off
	global_load_dwordx4 v[72:75], v[56:57], off offset:64
	global_load_dwordx4 v[80:83], v[56:57], off offset:128
	global_load_dwordx4 v[84:87], v[56:57], off offset:192
	v_add_u32_e32 v56, 16, v0
	v_min_i32_e32 v56, s0, v56
	v_ashrrev_i32_e32 v57, 31, v56
	v_lshlrev_b64 v[56:57], 7, v[56:57]
	v_cmp_lt_i32_e32 vcc, s1, v0
	s_movk_i32 s1, 0xffdf
	v_add_u32_e32 v102, 64, v0
	v_cndmask_b32_e32 v57, 0, v57, vcc
	v_cndmask_b32_e32 v56, 0, v56, vcc
	v_lshl_add_u64 v[56:57], v[56:57], 1, v[2:3]
	global_load_dwordx4 v[116:119], v[56:57], off
	global_load_dwordx4 v[136:139], v[56:57], off offset:64
	global_load_dwordx4 v[140:143], v[56:57], off offset:128
	global_load_dwordx4 v[144:147], v[56:57], off offset:192
	v_add_u32_e32 v56, 32, v0
	v_min_i32_e32 v56, s0, v56
	v_ashrrev_i32_e32 v57, 31, v56
	v_lshlrev_b64 v[56:57], 7, v[56:57]
	v_cmp_lt_i32_e32 vcc, s1, v0
	v_min_i32_e32 v100, s0, v102
	v_add_u32_e32 v122, 0x50, v0
	v_cndmask_b32_e32 v57, 0, v57, vcc
	v_cndmask_b32_e32 v56, 0, v56, vcc
	v_lshl_add_u64 v[56:57], v[56:57], 1, v[2:3]
	global_load_dwordx4 v[148:151], v[56:57], off
	global_load_dwordx4 v[152:155], v[56:57], off offset:64
	global_load_dwordx4 v[156:159], v[56:57], off offset:128
	global_load_dwordx4 v[160:163], v[56:57], off offset:192
	v_min_i32_e32 v56, s0, v58
	v_ashrrev_i32_e32 v57, 31, v56
	v_lshlrev_b64 v[56:57], 7, v[56:57]
	v_cmp_lt_i32_e32 vcc, -1, v58
	v_ashrrev_i32_e32 v101, 31, v100
	v_min_i32_e32 v120, s0, v122
	v_cndmask_b32_e32 v57, 0, v57, vcc
	v_cndmask_b32_e32 v56, 0, v56, vcc
	v_lshlrev_b64 v[100:101], 7, v[100:101]
	v_cmp_lt_i32_e32 vcc, -1, v102
	v_ashrrev_i32_e32 v121, 31, v120
	v_lshlrev_b64 v[120:121], 7, v[120:121]
	v_cndmask_b32_e32 v101, 0, v101, vcc
	v_cndmask_b32_e32 v100, 0, v100, vcc
	v_cmp_lt_i32_e32 vcc, -1, v122
	v_lshl_add_u64 v[76:77], v[56:57], 1, v[2:3]
	v_lshl_add_u64 v[112:113], v[100:101], 1, v[2:3]
	v_cndmask_b32_e32 v121, 0, v121, vcc
	v_cndmask_b32_e32 v120, 0, v120, vcc
	v_lshl_add_u64 v[132:133], v[120:121], 1, v[2:3]
	global_load_dwordx4 v[56:59], v[76:77], off
	global_load_dwordx4 v[60:63], v[76:77], off offset:64
	global_load_dwordx4 v[64:67], v[76:77], off offset:128
	s_nop 0
	global_load_dwordx4 v[76:79], v[76:77], off offset:192
	s_nop 0
	global_load_dwordx4 v[100:103], v[112:113], off
	global_load_dwordx4 v[104:107], v[112:113], off offset:64
	global_load_dwordx4 v[108:111], v[112:113], off offset:128
	s_nop 0
	global_load_dwordx4 v[112:115], v[112:113], off offset:192
	s_nop 0
	global_load_dwordx4 v[120:123], v[132:133], off
	global_load_dwordx4 v[124:127], v[132:133], off offset:64
	global_load_dwordx4 v[128:131], v[132:133], off offset:128
	s_nop 0
	global_load_dwordx4 v[132:135], v[132:133], off offset:192
	s_waitcnt vmcnt(23)
	v_mfma_f32_16x16x32_bf16 v[68:71], v[68:71], v[96:99], 0
	s_waitcnt vmcnt(22)
	v_mfma_f32_16x16x32_bf16 v[68:71], v[72:75], v[92:95], v[68:71]
	s_waitcnt vmcnt(21)
	v_mfma_f32_16x16x32_bf16 v[68:71], v[80:83], v[88:91], v[68:71]
	s_waitcnt vmcnt(20)
	v_mfma_f32_16x16x32_bf16 v[84:87], v[84:87], v[52:55], v[68:71]
	s_waitcnt vmcnt(19)
	v_mfma_f32_16x16x32_bf16 v[68:71], v[116:119], v[96:99], 0
	s_waitcnt vmcnt(18)
	v_mfma_f32_16x16x32_bf16 v[68:71], v[136:139], v[92:95], v[68:71]
	s_waitcnt vmcnt(17)
	v_mfma_f32_16x16x32_bf16 v[68:71], v[140:143], v[88:91], v[68:71]
	s_waitcnt vmcnt(16)
	v_mfma_f32_16x16x32_bf16 v[72:75], v[144:147], v[52:55], v[68:71]
	s_waitcnt vmcnt(15)
	v_mfma_f32_16x16x32_bf16 v[68:71], v[148:151], v[96:99], 0
	s_waitcnt vmcnt(14)
	v_mfma_f32_16x16x32_bf16 v[68:71], v[152:155], v[92:95], v[68:71]
	s_waitcnt vmcnt(13)
	v_mfma_f32_16x16x32_bf16 v[68:71], v[156:159], v[88:91], v[68:71]
	s_waitcnt vmcnt(12)
	v_mfma_f32_16x16x32_bf16 v[68:71], v[160:163], v[52:55], v[68:71]
	v_add_u32_e32 v82, 0x60, v0
	v_min_i32_e32 v80, s0, v82
	v_ashrrev_i32_e32 v81, 31, v80
	v_lshlrev_b64 v[80:81], 7, v[80:81]
	v_cmp_lt_i32_e32 vcc, -1, v82
	v_add_u32_e32 v82, 0x70, v0
	v_add_u32_e32 v0, 0x80, v0
	v_cndmask_b32_e32 v81, 0, v81, vcc
	v_cndmask_b32_e32 v80, 0, v80, vcc
	v_lshl_add_u64 v[80:81], v[80:81], 1, v[2:3]
	global_load_dwordx4 v[136:139], v[80:81], off
	global_load_dwordx4 v[140:143], v[80:81], off offset:64
	global_load_dwordx4 v[144:147], v[80:81], off offset:128
	global_load_dwordx4 v[148:151], v[80:81], off offset:192
	v_min_i32_e32 v80, s0, v82
	v_ashrrev_i32_e32 v81, 31, v80
	v_lshlrev_b64 v[80:81], 7, v[80:81]
	v_cmp_lt_i32_e32 vcc, -1, v82
	s_cmpk_gt_i32 s14, 0x11ff
	s_nop 0
	v_cndmask_b32_e32 v81, 0, v81, vcc
	v_cndmask_b32_e32 v80, 0, v80, vcc
	v_lshl_add_u64 v[80:81], v[80:81], 1, v[2:3]
	global_load_dwordx4 v[152:155], v[80:81], off
	global_load_dwordx4 v[156:159], v[80:81], off offset:64
	global_load_dwordx4 v[160:163], v[80:81], off offset:128
	global_load_dwordx4 v[164:167], v[80:81], off offset:192
	v_min_i32_e32 v80, s0, v0
	v_ashrrev_i32_e32 v81, 31, v80
	v_lshlrev_b64 v[80:81], 7, v[80:81]
	v_cmp_lt_i32_e32 vcc, -1, v0
	s_nop 1
	v_cndmask_b32_e32 v81, 0, v81, vcc
	v_cndmask_b32_e32 v80, 0, v80, vcc
	v_lshl_add_u64 v[2:3], v[80:81], 1, v[2:3]
	global_load_dwordx4 v[176:179], v[2:3], off
	global_load_dwordx4 v[172:175], v[2:3], off offset:64
	global_load_dwordx4 v[168:171], v[2:3], off offset:128
	global_load_dwordx4 v[116:119], v[2:3], off offset:192
	s_cbranch_scc1 .LBB0_451
; #define ATT_MMAK(buf, grp) do { _Pragma("unroll") for (int tt = 0; tt < 3; ++tt) { f32x4 acc_ = (f32x4){0.f, 0.f, 0.f, 0.f}; \
;             _Pragma("unroll") for (int ks = 0; ks < 4; ++ks) acc_ = __builtin_amdgcn_mfma_f32_16x16x32_bf16(Kf[buf][tt][ks], Qf[ks], acc_, 0, 0, 0); sa[(grp) * 3 + tt] = acc_; } } while (0)
; __device__ __forceinline__ void attn_load_v(const AttnItem& a, const bf16_t* qkv, int ht, u32x4 (&vreg)[12]) {
; #pragma unroll
;     for (int pass = 0; pass < 12; ++pass) {
;         const int row = pass * 16 + (ht >> 4), ch = ht & 15, ki = a.i0 - 64 + row;
;         u32x4 val = (u32x4){0u, 0u, 0u, 0u};
;         if (ki >= 0 && ki < a.m) val = *(const u32x4*)(qkv + ((size_t)(24 + a.head) * M_TOK + a.seq_base + a.r * a.m + ki) * 128 + ch * 8);
;         vreg[pass] = val;
;     }
; }
; __device__ __forceinline__ void attn_phase(LAS unsigned char* lds, bf16_t* qkv, float* lse, const float* biasT, int G) {
;     ...
;         if (pairn < 4608) { const AttnItem an = attn_item(pairn * 2 + half); attn_load_v(an, qkv, ht, vreg); }
;         __builtin_amdgcn_sched_barrier(0);
;         ATT_MMAK(1, 1);
;         ATT_MMAK(0, 2);
;     ...
;         sa[9] = (f32x4){0.f, 0.f, 0.f, 0.f};
;         const int kabs0 = a.i0 - 64 + 16 * w4 + 4 * lg;
;         const bool edge = (a.i0 == 0) || (a.i0 + 64 == a.m);
	s_lshl_b32 s0, s14, 1
	s_add_i32 s0, s0, s94
	s_mul_hi_i32 s1, s0, 0x2aaaaaab
	s_lshr_b32 s14, s1, 31
	s_ashr_i32 s1, s1, 7
	s_add_i32 s14, s1, s14
	s_mul_i32 s1, s14, 0xfffffd00
	s_add_i32 s1, s1, s0
	s_lshl_b32 s0, s1, 6
	s_and_b32 s16, s0, 0xffffe000
	s_cmpk_lt_i32 s1, 0x200
	s_cselect_b32 s1, 13, 14
	s_cselect_b32 s16, s16, 0x8000
	s_ashr_i32 s17, s14, 1
	s_and_b32 s17, s17, -2
	s_sub_i32 s1, s1, s17
	s_lshl_b32 s18, 1, s1
	s_sub_i32 s0, s0, s16
	s_lshl_b32 s1, -1, s1
	s_and_b32 s17, s1, s0
	s_sub_i32 s19, s0, s17
	s_cmp_lt_i32 s19, 64
	s_cbranch_scc1 .Lattn_vslow
	s_add_i32 s0, s19, 0x80
	s_cmp_gt_i32 s0, s18
	s_cbranch_scc1 .Lattn_vslow
	s_add_i32 s28, s14, 24
	s_mul_i32 s28, s28, 0xc000
	s_add_i32 s28, s28, s16
	s_add_i32 s28, s28, s17
	s_add_i32 s28, s28, s19
	v_add_u32_e32 v0, s28, v220
	v_lshlrev_b32_e32 v0, 8, v0
	s_mov_b64 s[28:29], 0x1000
	v_lshl_add_u64 v[2:3], v[188:189], 0, v[0:1]
	v_lshl_add_u64 v[2:3], s[28:29], 0, v[2:3]
	s_mov_b64 s[28:29], 0x2000
	global_load_dwordx4 v[8:11], v[2:3], off offset:-4096
	global_load_dwordx4 v[4:7], v[2:3], off
	v_lshl_add_u64 v[2:3], s[28:29], 0, v[2:3]
	global_load_dwordx4 v[12:15], v[2:3], off offset:-4096
	global_load_dwordx4 v[16:19], v[2:3], off
	v_lshl_add_u64 v[2:3], s[28:29], 0, v[2:3]
	global_load_dwordx4 v[20:23], v[2:3], off offset:-4096
	global_load_dwordx4 v[24:27], v[2:3], off
	v_lshl_add_u64 v[2:3], s[28:29], 0, v[2:3]
	global_load_dwordx4 v[28:31], v[2:3], off offset:-4096
	global_load_dwordx4 v[32:35], v[2:3], off
	v_lshl_add_u64 v[2:3], s[28:29], 0, v[2:3]
	global_load_dwordx4 v[36:39], v[2:3], off offset:-4096
	global_load_dwordx4 v[40:43], v[2:3], off
	v_lshl_add_u64 v[2:3], s[28:29], 0, v[2:3]
	global_load_dwordx4 v[44:47], v[2:3], off offset:-4096
	global_load_dwordx4 v[48:51], v[2:3], off
	s_lshl_b32 s14, 1, s11
	s_ashr_i32 s11, s10, 31
	s_waitcnt vmcnt(35)
	v_mfma_f32_16x16x32_bf16 v[56:59], v[56:59], v[96:99], 0
	s_cmp_eq_u32 s30, s31
	s_cselect_b64 s[0:1], -1, 0
	s_add_i32 s16, s13, 64
	s_waitcnt vmcnt(34)
	v_mfma_f32_16x16x32_bf16 v[56:59], v[60:63], v[92:95], v[56:59]
	s_cmp_eq_u32 s16, s14
	s_cselect_b64 s[16:17], -1, 0
	s_or_b64 s[16:17], s[0:1], s[16:17]
	s_waitcnt vmcnt(33)
	v_mfma_f32_16x16x32_bf16 v[56:59], v[64:67], v[88:91], v[56:59]
	s_mov_b64 s[0:1], -1
	s_andn2_b64 vcc, exec, s[16:17]
	s_waitcnt vmcnt(32)
	v_mfma_f32_16x16x32_bf16 v[80:83], v[76:79], v[52:55], v[56:59]
	s_waitcnt vmcnt(31)
	v_mfma_f32_16x16x32_bf16 v[56:59], v[100:103], v[96:99], 0
	s_waitcnt vmcnt(30)
	v_mfma_f32_16x16x32_bf16 v[56:59], v[104:107], v[92:95], v[56:59]
	s_waitcnt vmcnt(29)
	v_mfma_f32_16x16x32_bf16 v[56:59], v[108:111], v[88:91], v[56:59]
	s_waitcnt vmcnt(28)
	v_mfma_f32_16x16x32_bf16 v[76:79], v[112:115], v[52:55], v[56:59]
	s_waitcnt vmcnt(27)
	v_mfma_f32_16x16x32_bf16 v[56:59], v[120:123], v[96:99], 0
	s_waitcnt vmcnt(26)
	v_mfma_f32_16x16x32_bf16 v[56:59], v[124:127], v[92:95], v[56:59]
	s_waitcnt vmcnt(25)
	v_mfma_f32_16x16x32_bf16 v[56:59], v[128:131], v[88:91], v[56:59]
	s_waitcnt vmcnt(24)
	v_mfma_f32_16x16x32_bf16 v[64:67], v[132:135], v[52:55], v[56:59]
	s_waitcnt vmcnt(23)
	v_mfma_f32_16x16x32_bf16 v[56:59], v[136:139], v[96:99], 0
	s_waitcnt vmcnt(22)
	v_mfma_f32_16x16x32_bf16 v[56:59], v[140:143], v[92:95], v[56:59]
	s_waitcnt vmcnt(21)
	v_mfma_f32_16x16x32_bf16 v[56:59], v[144:147], v[88:91], v[56:59]
	s_waitcnt vmcnt(20)
	v_mfma_f32_16x16x32_bf16 v[60:63], v[148:151], v[52:55], v[56:59]
	s_waitcnt vmcnt(19)
	v_mfma_f32_16x16x32_bf16 v[56:59], v[152:155], v[96:99], 0
	s_waitcnt vmcnt(15)
	v_mfma_f32_16x16x32_bf16 v[96:99], v[176:179], v[96:99], 0
	v_mfma_f32_16x16x32_bf16 v[56:59], v[156:159], v[92:95], v[56:59]
	s_waitcnt vmcnt(14)
	v_mfma_f32_16x16x32_bf16 v[92:95], v[172:175], v[92:95], v[96:99]
	v_mfma_f32_16x16x32_bf16 v[56:59], v[160:163], v[88:91], v[56:59]
	s_waitcnt vmcnt(13)
	v_mfma_f32_16x16x32_bf16 v[126:129], v[168:171], v[88:91], v[92:95]
	v_mfma_f32_16x16x32_bf16 v[56:59], v[164:167], v[52:55], v[56:59]
	s_waitcnt vmcnt(12)
	v_mfma_f32_16x16x32_bf16 v[52:55], v[116:119], v[52:55], v[126:129]
	s_branch .Lattn_mm_join

; #define LAS __attribute__((address_space(3)))
; template <bool EDGE>
; __device__ __forceinline__ float attn_scores(f32x4 (&sa)[10], const LAS float* bsl, int dl, int kabs0, int m, float scale2) {
;     float mx = -3.0e38f;
; #pragma unroll
;     for (int t9 = 0; t9 < 9; ++t9)
; #pragma unroll
;         for (int j = 0; j < 4; ++j) {
;             bool valid = true;
;             if (t9 == 0) valid = (j + dl >= 0);
;             if (t9 == 8) valid = (j + dl <= 0);
;             if (EDGE) { const int kabs = kabs0 + 16 * t9 + j; valid = valid && (kabs >= 0) && (kabs < m); }
;             float sv = sa[t9][j] * scale2 + bsl[16 * t9 + j];
;             sv = valid ? sv : -1.0e30f;
;             sa[t9][j] = sv; mx = fmaxf(mx, sv);
;         }
;     return mx;
; }
; __device__ __forceinline__ void attn_phase(LAS unsigned char* lds, bf16_t* qkv, float* lse, const float* biasT, int G) {
;     ...
;         const bool edge = (a.i0 == 0) || (a.i0 + 64 == a.m);
;         float mx = edge ? attn_scores<true>(sa, bsl, dl, kabs0, a.m, scale2) : attn_scores<false>(sa, bsl, dl, kabs0, a.m, scale2);
.Lattn_mm_join:
	s_waitcnt lgkmcnt(0)
	s_barrier
	s_cbranch_vccz .LBB0_453
	ds_read2_b32 v[2:3], v218 offset0:16 offset1:17
	s_mov_b32 s0, 0x3e0293ee
	v_readlane_b32 s16, v250, 22
	v_readlane_b32 s17, v250, 23
	s_waitcnt lgkmcnt(0)
	v_pk_fma_f32 v[2:3], v[84:85], s[0:1], v[2:3] op_sel_hi:[1,0,1]
	s_nop 0
	v_cndmask_b32_e64 v0, v212, v3, s[16:17]
	v_readlane_b32 s16, v250, 17
	v_readlane_b32 s17, v250, 18
	s_nop 1
	v_cndmask_b32_e64 v114, v212, v2, s[16:17]
	ds_read2_b32 v[2:3], v218 offset0:18 offset1:19
	v_readlane_b32 s16, v250, 24
	v_readlane_b32 s17, v250, 25
	v_max_f32_e32 v88, 0xff61b1e6, v114
	s_waitcnt lgkmcnt(0)
	v_pk_fma_f32 v[2:3], v[86:87], s[0:1], v[2:3] op_sel_hi:[1,0,1]
	s_nop 0
	v_cndmask_b32_e64 v120, v212, v3, s[16:17]
	v_readlane_b32 s16, v251, 63
	v_readlane_b32 s17, v250, 0
	s_nop 1
	v_cndmask_b32_e64 v115, v212, v2, s[16:17]
	ds_read2_b32 v[2:3], v218 offset0:32 offset1:33
	v_max3_f32 v88, v88, v0, v115
	s_waitcnt lgkmcnt(0)
	v_pk_fma_f32 v[2:3], v[72:73], s[0:1], v[2:3] op_sel_hi:[1,0,1]
	s_nop 0
	v_max3_f32 v90, v88, v120, v2
	ds_read2_b32 v[88:89], v218 offset0:34 offset1:35
	s_waitcnt lgkmcnt(0)
	v_pk_fma_f32 v[88:89], v[74:75], s[0:1], v[88:89] op_sel_hi:[1,0,1]
	s_nop 0
	v_max3_f32 v92, v90, v3, v88
	ds_read2_b32 v[90:91], v218 offset0:48 offset1:49
	s_waitcnt lgkmcnt(0)
	v_pk_fma_f32 v[90:91], v[68:69], s[0:1], v[90:91] op_sel_hi:[1,0,1]
	s_nop 0
	v_max3_f32 v94, v92, v89, v90
	ds_read2_b32 v[92:93], v218 offset0:50 offset1:51
	s_waitcnt lgkmcnt(0)
	v_pk_fma_f32 v[92:93], v[70:71], s[0:1], v[92:93] op_sel_hi:[1,0,1]
	s_nop 0
	v_max3_f32 v96, v94, v91, v92
	ds_read2_b32 v[94:95], v218 offset0:64 offset1:65
	s_waitcnt lgkmcnt(0)
	v_pk_fma_f32 v[94:95], v[80:81], s[0:1], v[94:95] op_sel_hi:[1,0,1]
	s_nop 0
	v_max3_f32 v98, v96, v93, v94
	ds_read2_b32 v[96:97], v218 offset0:66 offset1:67
	s_waitcnt lgkmcnt(0)
	v_pk_fma_f32 v[96:97], v[82:83], s[0:1], v[96:97] op_sel_hi:[1,0,1]
	s_nop 0
	v_max3_f32 v100, v98, v95, v96
	ds_read2_b32 v[98:99], v218 offset0:80 offset1:81
	s_waitcnt lgkmcnt(0)
	v_pk_fma_f32 v[98:99], v[76:77], s[0:1], v[98:99] op_sel_hi:[1,0,1]
	s_nop 0
	v_max3_f32 v102, v100, v97, v98
	ds_read2_b32 v[100:101], v218 offset0:82 offset1:83
	s_waitcnt lgkmcnt(0)
	v_pk_fma_f32 v[100:101], v[78:79], s[0:1], v[100:101] op_sel_hi:[1,0,1]
	s_nop 0
	v_max3_f32 v104, v102, v99, v100
	ds_read2_b32 v[102:103], v218 offset0:96 offset1:97
	s_waitcnt lgkmcnt(0)
	v_pk_fma_f32 v[102:103], v[64:65], s[0:1], v[102:103] op_sel_hi:[1,0,1]
	s_nop 0
	v_max3_f32 v106, v104, v101, v102
	ds_read2_b32 v[104:105], v218 offset0:98 offset1:99
	s_waitcnt lgkmcnt(0)
	v_pk_fma_f32 v[104:105], v[66:67], s[0:1], v[104:105] op_sel_hi:[1,0,1]
	s_nop 0
	v_max3_f32 v108, v106, v103, v104
	ds_read2_b32 v[106:107], v218 offset0:112 offset1:113
	s_waitcnt lgkmcnt(0)
	v_pk_fma_f32 v[106:107], v[60:61], s[0:1], v[106:107] op_sel_hi:[1,0,1]
	s_nop 0
	v_max3_f32 v110, v108, v105, v106
	ds_read2_b32 v[108:109], v218 offset0:114 offset1:115
	s_waitcnt lgkmcnt(0)
	v_pk_fma_f32 v[108:109], v[62:63], s[0:1], v[108:109] op_sel_hi:[1,0,1]
	s_nop 0
	v_max3_f32 v112, v110, v107, v108
	ds_read2_b32 v[110:111], v218 offset0:128 offset1:129
	s_waitcnt lgkmcnt(0)
	v_pk_fma_f32 v[110:111], v[56:57], s[0:1], v[110:111] op_sel_hi:[1,0,1]
	s_nop 0
	v_max3_f32 v116, v112, v109, v110
	ds_read2_b32 v[112:113], v218 offset0:130 offset1:131
	s_waitcnt lgkmcnt(0)
	v_pk_fma_f32 v[112:113], v[58:59], s[0:1], v[112:113] op_sel_hi:[1,0,1]
	s_nop 0
	v_max3_f32 v118, v116, v111, v112
	ds_read2_b32 v[116:117], v218 offset0:144 offset1:145
	s_waitcnt lgkmcnt(0)
	v_pk_fma_f32 v[116:117], v[52:53], s[0:1], v[116:117] op_sel_hi:[1,0,1]
	v_readlane_b32 s0, v250, 11
	v_readlane_b32 s1, v250, 12
	s_nop 1
	v_cndmask_b32_e64 v121, v212, v117, s[0:1]
	ds_read_b32 v117, v218 offset:584
	v_readlane_b32 s0, v250, 9
	v_readlane_b32 s1, v250, 10
	s_waitcnt lgkmcnt(0)
	v_fmac_f32_e32 v117, 0x3e0293ee, v54
	v_cndmask_b32_e64 v122, v212, v116, s[0:1]
	v_max3_f32 v116, v118, v113, v122
	v_cndmask_b32_e64 v123, v212, v117, s[22:23]
	v_max3_f32 v124, v116, v121, v123
	s_mov_b64 s[0:1], 0

; template <bool COOP>
; __global__ void __launch_bounds__(512, 2) fwd_kernel(Params p) {
;     ...
;     }
; }
.LBB0_641:
	s_nop 0
	s_nop 0
	s_nop 0
	s_nop 0
	s_nop 0
	s_nop 0
	s_nop 0
	s_nop 0
	s_nop 0
	s_nop 0
	s_nop 0
	s_nop 0
	s_nop 0
	s_nop 0
	s_nop 0
	s_nop 0
	s_nop 0
	s_nop 0
	s_nop 0
	s_nop 0
	s_nop 0
	s_nop 0
	s_nop 0
	s_nop 0
	s_nop 0
	s_nop 0
	s_nop 0
	s_nop 0
	s_nop 0
	s_nop 0
	s_nop 0
	s_nop 0
	s_nop 0
	s_nop 0
	s_nop 0
	s_nop 0
	s_nop 0
	s_nop 0
	s_nop 0
	s_nop 0
	s_nop 0
	s_nop 0
	s_nop 0
	s_nop 0
	s_nop 0
	s_nop 0
	s_nop 0
	s_nop 0
	s_nop 0
	s_nop 0
	s_nop 0
	s_nop 0
	s_nop 0
	s_nop 0
	s_nop 0
	s_nop 0
	s_nop 0
	s_nop 0
	s_nop 0
	s_nop 0
	s_nop 0
	s_nop 0
	s_nop 0
	s_nop 0
	s_nop 0
	s_nop 0
	s_nop 0
	s_nop 0
	s_nop 0
	s_nop 0
	s_nop 0
	s_nop 0
	s_nop 0
	s_nop 0
	s_nop 0
	s_nop 0
	s_nop 0
	s_nop 0
	s_nop 0
	s_nop 0
	s_nop 0
	s_nop 0
	s_nop 0
	s_nop 0
	s_nop 0
	s_nop 0
	s_nop 0
	s_nop 0
	s_nop 0
	s_nop 0
	s_nop 0
	s_nop 0
	s_nop 0
	s_nop 0
	s_nop 0
	s_nop 0
	s_nop 0
	s_nop 0
	s_nop 0
	s_nop 0
	s_nop 0
	s_nop 0
	s_nop 0
	s_nop 0
	s_nop 0
	s_nop 0
	s_nop 0
	s_nop 0
	s_nop 0
	s_nop 0
	s_nop 0
	s_nop 0
	s_nop 0
	s_nop 0
	s_nop 0
	s_nop 0
	s_nop 0
	s_nop 0
	s_nop 0
	s_nop 0
	s_nop 0
	s_nop 0
	s_nop 0
	s_nop 0
	s_nop 0
	s_nop 0
	s_nop 0
	s_nop 0
	s_nop 0
	s_nop 0
	s_nop 0
	s_nop 0
	s_nop 0
	s_nop 0
	s_nop 0
	s_nop 0
	s_nop 0
	s_nop 0
	s_nop 0
	s_nop 0
	s_nop 0
	s_nop 0
	s_nop 0
	s_nop 0
	s_nop 0
	s_nop 0
	s_nop 0
	s_nop 0
	s_nop 0
	s_nop 0
	s_nop 0
	s_nop 0
	s_nop 0
	s_nop 0
	s_nop 0
	s_nop 0
	s_nop 0
	s_nop 0
	s_nop 0
	s_nop 0
	s_nop 0
	s_nop 0
	s_nop 0
	s_nop 0
	s_nop 0
	s_nop 0
	s_nop 0
	s_nop 0
	s_nop 0
	s_nop 0
	s_nop 0
	s_nop 0
	s_nop 0
	s_nop 0
	s_nop 0
	s_nop 0
	s_nop 0
	s_nop 0
	s_nop 0
	s_nop 0
	s_nop 0
	s_endpgm
